# remove compiler-inserted s_waitcnt vmcnt(0) at top of m1 w_in GEMM K-loop (other 6 GEMM loops never had it)
# speedup vs baseline: 1.0082x; 1.0014x over previous
; #define PG8_STAGE(bufoff, gbase, voff) do { _Pragma("unroll") for (int _i = 0; _i < 2; ++_i) \
;         __builtin_amdgcn_global_load_lds((const unsigned*)((const char*)(gbase) + (voff)[_i]), (LAS unsigned*)(lds + (bufoff) + ldsw + _i * 8192), 16, 0, 0); } while (0)
; #define PG8_LDA(dst, b, h) do { _Pragma("unroll") for (int m = 0; m < 4; ++m) _Pragma("unroll") for (int k = 0; k < 2; ++k) dst[m][k] = *(const LAS bf16x8*)(lds + PG8_SA(b, h) + aoff + m * 2048 + k * 1024); } while (0)
; #define PG8_LDB(dst, b, h) do { _Pragma("unroll") for (int n = 0; n < 2; ++n) _Pragma("unroll") for (int k = 0; k < 2; ++k) dst[n][k] = *(const LAS bf16x8*)(lds + PG8_SB(b, h) + boff + n * 2048 + k * 1024); } while (0)
; #define PG8_MMA(ai, bj, At, Bt) do { __builtin_amdgcn_s_setprio(1); _Pragma("unroll") for (int m = 0; m < 4; ++m) _Pragma("unroll") for (int n = 0; n < 2; ++n) _Pragma("unroll") for (int k = 0; k < 2; ++k) \
;         acc[ai][bj][m][n] = __builtin_amdgcn_mfma_f32_16x16x32_bf16(Bt[n][k], At[m][k], acc[ai][bj][m][n], 0, 0, 0); __builtin_amdgcn_s_setprio(0); } while (0)
; #define PG8_WAIT_V(n) asm volatile("s_waitcnt vmcnt(" #n ")" ::: "memory")
; #define PG8_WAIT_L(n) asm volatile("s_waitcnt lgkmcnt(" #n ")" ::: "memory")
; #define PG8_BAR __builtin_amdgcn_s_barrier()
; #define PG8_SCHED __builtin_amdgcn_sched_barrier(0)
; template <class Epi, class Sched>
; __device__ __forceinline__ void gemm_phase(const int tid, LAS unsigned char* lds, const Gemm g, const Sched& S, const Epi& E) {
;     ...
;         for (int t = 0; t < nt; t += 2) {
;             const bool last = (t == nt - 2);
;             const char* a1 = cA + (size_t)(t + 1) * kstepA;
;             const char* a2 = last ? nA : cA + (size_t)(t + 2) * kstepA; const char* b2 = last ? nB : cB + (size_t)(t + 2) * kstepB;
;             const char* a3 = a2 + kstepA; const char* b3 = b2 + kstepB;
;             PG8_LDB(B0, 0, 0); PG8_LDB(B1, 0, 1); PG8_SCHED; PG8_LDA(At, 0, 0); PG8_STAGE(PG8_SA(1, 1), a1 + hstepA, voffA);
;             PG8_WAIT_V(8); PG8_WAIT_L(0); PG8_BAR; PG8_MMA(0, 0, At, B0); PG8_MMA(0, 1, At, B1); PG8_BAR; PG8_SCHED;
;             PG8_LDA(At, 0, 1); PG8_STAGE(PG8_SB(0, 0), b2, voffB); PG8_STAGE(PG8_SB(0, 1), b2 + hstepB, voffB); PG8_STAGE(PG8_SA(0, 0), a2, voffA);
;             PG8_WAIT_V(8); PG8_WAIT_L(0); PG8_BAR; PG8_MMA(1, 0, At, B0); PG8_MMA(1, 1, At, B1); PG8_BAR; PG8_SCHED;
.LBB0_135:
	s_add_u32 s24, s6, 0x4000
	s_addc_u32 s25, s7, 0
	s_cmp_eq_u32 s66, 28
	s_cselect_b32 s28, s19, s24
	s_cselect_b32 s29, s13, s25
	s_cselect_b32 s26, s63, s64
	s_cselect_b32 s27, s17, s65
	s_add_u32 s24, s28, 0x8000
	s_addc_u32 s25, s29, 0
	s_add_i32 s67, 16, 0x10000
	s_add_i32 s78, 16, 0x14000
	v_add_u32_e32 v78, s67, v180
	v_add_u32_e32 v178, s78, v180
	ds_read_b128 v[58:61], v78
	ds_read_b128 v[62:65], v78 offset:1024
	ds_read_b128 v[74:77], v78 offset:2048
	ds_read_b128 v[78:81], v78 offset:3072
	ds_read_b128 v[174:177], v178
	ds_read_b128 v[182:185], v178 offset:1024
	ds_read_b128 v[186:189], v178 offset:2048
	ds_read_b128 v[190:193], v178 offset:3072
	s_add_i32 m0, s15, 0xc000
	ds_read_b128 v[208:211], v181
	ds_read_b128 v[212:215], v181 offset:1024
	ds_read_b128 v[216:219], v181 offset:2048
	ds_read_b128 v[220:223], v181 offset:3072
	ds_read_b128 v[236:239], v181 offset:4096
	ds_read_b128 v[244:247], v181 offset:5120
	ds_read_b128 v[248:251], v181 offset:6144
	ds_read_b128 v[204:207], v181 offset:7168
	global_load_lds_dwordx4 v172, s[6:7]
	s_add_i32 m0, s15, 0xe000
	s_nop 0
	global_load_lds_dwordx4 v170, s[6:7]
	s_waitcnt vmcnt(8)
	s_waitcnt lgkmcnt(0)
	s_barrier
	s_setprio 1
	s_waitcnt lgkmcnt(0)
	v_mfma_f32_16x16x32_bf16 v[142:145], v[58:61], v[208:211], v[142:145]
	v_mfma_f32_16x16x32_bf16 v[138:141], v[74:77], v[208:211], v[138:141]
	v_mfma_f32_16x16x32_bf16 v[126:129], v[58:61], v[216:219], v[126:129]
	v_mfma_f32_16x16x32_bf16 v[122:125], v[74:77], v[216:219], v[122:125]
	v_mfma_f32_16x16x32_bf16 v[110:113], v[58:61], v[236:239], v[110:113]
	v_mfma_f32_16x16x32_bf16 v[106:109], v[74:77], v[236:239], v[106:109]
	v_mfma_f32_16x16x32_bf16 v[94:97], v[58:61], v[248:251], v[94:97]
	v_mfma_f32_16x16x32_bf16 v[90:93], v[74:77], v[248:251], v[90:93]
	v_mfma_f32_16x16x32_bf16 v[142:145], v[62:65], v[212:215], v[142:145]
	v_mfma_f32_16x16x32_bf16 v[138:141], v[78:81], v[212:215], v[138:141]
	v_mfma_f32_16x16x32_bf16 v[126:129], v[62:65], v[220:223], v[126:129]
	v_mfma_f32_16x16x32_bf16 v[122:125], v[78:81], v[220:223], v[122:125]
	v_mfma_f32_16x16x32_bf16 v[110:113], v[62:65], v[244:247], v[110:113]
	v_mfma_f32_16x16x32_bf16 v[106:109], v[78:81], v[244:247], v[106:109]
	v_mfma_f32_16x16x32_bf16 v[94:97], v[62:65], v[204:207], v[94:97]
	v_mfma_f32_16x16x32_bf16 v[90:93], v[78:81], v[204:207], v[90:93]
	v_mfma_f32_16x16x32_bf16 v[134:137], v[174:177], v[208:211], v[134:137]
	v_mfma_f32_16x16x32_bf16 v[130:133], v[186:189], v[208:211], v[130:133]
	v_mfma_f32_16x16x32_bf16 v[118:121], v[174:177], v[216:219], v[118:121]
	v_mfma_f32_16x16x32_bf16 v[114:117], v[186:189], v[216:219], v[114:117]
	v_mfma_f32_16x16x32_bf16 v[102:105], v[174:177], v[236:239], v[102:105]
	v_mfma_f32_16x16x32_bf16 v[98:101], v[186:189], v[236:239], v[98:101]
	v_mfma_f32_16x16x32_bf16 v[86:89], v[174:177], v[248:251], v[86:89]
	v_mfma_f32_16x16x32_bf16 v[82:85], v[186:189], v[248:251], v[82:85]
	v_mfma_f32_16x16x32_bf16 v[134:137], v[182:185], v[212:215], v[134:137]
	v_mfma_f32_16x16x32_bf16 v[130:133], v[190:193], v[212:215], v[130:133]
	v_mfma_f32_16x16x32_bf16 v[118:121], v[182:185], v[220:223], v[118:121]
	v_mfma_f32_16x16x32_bf16 v[114:117], v[190:193], v[220:223], v[114:117]
	v_mfma_f32_16x16x32_bf16 v[102:105], v[182:185], v[244:247], v[102:105]
	v_mfma_f32_16x16x32_bf16 v[98:101], v[190:193], v[244:247], v[98:101]
	v_mfma_f32_16x16x32_bf16 v[86:89], v[182:185], v[204:207], v[86:89]
	v_mfma_f32_16x16x32_bf16 v[82:85], v[190:193], v[204:207], v[82:85]
	s_setprio 0
	s_barrier
	s_add_i32 s67, s67, s54
	s_mov_b32 m0, s67
	ds_read_b128 v[204:207], v181 offset:16384
	ds_read_b128 v[208:211], v181 offset:17408
	ds_read_b128 v[212:215], v181 offset:18432
	ds_read_b128 v[216:219], v181 offset:19456
	ds_read_b128 v[220:223], v181 offset:20480
	ds_read_b128 v[236:239], v181 offset:21504
	ds_read_b128 v[244:247], v181 offset:22528
	ds_read_b128 v[248:251], v181 offset:23552
	global_load_lds_dwordx4 v0, s[26:27]
	s_add_i32 m0, s67, 0x2000
	s_add_u32 s76, s26, 0x4000
	s_addc_u32 s77, s27, 0
	s_add_i32 s67, s78, s54
	global_load_lds_dwordx4 v150, s[26:27]
	s_mov_b32 m0, s67
	s_nop 0
	global_load_lds_dwordx4 v0, s[76:77]
	s_add_i32 m0, s67, 0x2000
	s_nop 0
	global_load_lds_dwordx4 v150, s[76:77]
	s_mov_b32 m0, s15
	s_nop 0
	global_load_lds_dwordx4 v146, s[28:29]
	v_lshl_add_u64 v[178:179], s[28:29], 0, v[148:149]
	s_mov_b32 m0, s55
	s_nop 0
	global_load_lds_dwordx4 v[178:179], off
	s_waitcnt vmcnt(8)
	s_waitcnt lgkmcnt(0)
	s_barrier
	s_setprio 1
	s_waitcnt lgkmcnt(0)
	v_mfma_f32_16x16x32_bf16 v[70:73], v[58:61], v[204:207], v[70:73]
	v_mfma_f32_16x16x32_bf16 v[66:69], v[74:77], v[204:207], v[66:69]
	v_mfma_f32_16x16x32_bf16 v[46:49], v[58:61], v[212:215], v[46:49]
	v_mfma_f32_16x16x32_bf16 v[42:45], v[74:77], v[212:215], v[42:45]
	v_mfma_f32_16x16x32_bf16 v[30:33], v[58:61], v[220:223], v[30:33]
	v_mfma_f32_16x16x32_bf16 v[26:29], v[74:77], v[220:223], v[26:29]
	v_mfma_f32_16x16x32_bf16 v[14:17], v[58:61], v[244:247], v[14:17]
	v_mfma_f32_16x16x32_bf16 v[10:13], v[74:77], v[244:247], v[10:13]
	v_mfma_f32_16x16x32_bf16 v[70:73], v[62:65], v[208:211], v[70:73]
	v_mfma_f32_16x16x32_bf16 v[66:69], v[78:81], v[208:211], v[66:69]
	v_mfma_f32_16x16x32_bf16 v[46:49], v[62:65], v[216:219], v[46:49]
	v_mfma_f32_16x16x32_bf16 v[42:45], v[78:81], v[216:219], v[42:45]
	v_mfma_f32_16x16x32_bf16 v[30:33], v[62:65], v[236:239], v[30:33]
	v_mfma_f32_16x16x32_bf16 v[26:29], v[78:81], v[236:239], v[26:29]
	v_mfma_f32_16x16x32_bf16 v[14:17], v[62:65], v[248:251], v[14:17]
	v_mfma_f32_16x16x32_bf16 v[10:13], v[78:81], v[248:251], v[10:13]
	v_mfma_f32_16x16x32_bf16 v[54:57], v[174:177], v[204:207], v[54:57]
	v_mfma_f32_16x16x32_bf16 v[50:53], v[186:189], v[204:207], v[50:53]
	v_mfma_f32_16x16x32_bf16 v[38:41], v[174:177], v[212:215], v[38:41]
	v_mfma_f32_16x16x32_bf16 v[34:37], v[186:189], v[212:215], v[34:37]
	v_mfma_f32_16x16x32_bf16 v[22:25], v[174:177], v[220:223], v[22:25]
	v_mfma_f32_16x16x32_bf16 v[18:21], v[186:189], v[220:223], v[18:21]
	v_mfma_f32_16x16x32_bf16 v[6:9], v[174:177], v[244:247], v[6:9]
	v_mfma_f32_16x16x32_bf16 v[2:5], v[186:189], v[244:247], v[2:5]
	v_mfma_f32_16x16x32_bf16 v[54:57], v[182:185], v[208:211], v[54:57]
	v_mfma_f32_16x16x32_bf16 v[50:53], v[190:193], v[208:211], v[50:53]
	v_mfma_f32_16x16x32_bf16 v[38:41], v[182:185], v[216:219], v[38:41]
	v_mfma_f32_16x16x32_bf16 v[34:37], v[190:193], v[216:219], v[34:37]
	v_mfma_f32_16x16x32_bf16 v[22:25], v[182:185], v[236:239], v[22:25]
	v_mfma_f32_16x16x32_bf16 v[18:21], v[190:193], v[236:239], v[18:21]
	v_mfma_f32_16x16x32_bf16 v[6:9], v[182:185], v[248:251], v[6:9]
	v_mfma_f32_16x16x32_bf16 v[2:5], v[190:193], v[248:251], v[2:5]
	s_setprio 0
	s_barrier
; #define PG8_STAGE(bufoff, gbase, voff) do { _Pragma("unroll") for (int _i = 0; _i < 2; ++_i) \
;         __builtin_amdgcn_global_load_lds((const unsigned*)((const char*)(gbase) + (voff)[_i]), (LAS unsigned*)(lds + (bufoff) + ldsw + _i * 8192), 16, 0, 0); } while (0)
; #define PG8_LDA(dst, b, h) do { _Pragma("unroll") for (int m = 0; m < 4; ++m) _Pragma("unroll") for (int k = 0; k < 2; ++k) dst[m][k] = *(const LAS bf16x8*)(lds + PG8_SA(b, h) + aoff + m * 2048 + k * 1024); } while (0)
; #define PG8_LDB(dst, b, h) do { _Pragma("unroll") for (int n = 0; n < 2; ++n) _Pragma("unroll") for (int k = 0; k < 2; ++k) dst[n][k] = *(const LAS bf16x8*)(lds + PG8_SB(b, h) + boff + n * 2048 + k * 1024); } while (0)
; #define PG8_MMA(ai, bj, At, Bt) do { __builtin_amdgcn_s_setprio(1); _Pragma("unroll") for (int m = 0; m < 4; ++m) _Pragma("unroll") for (int n = 0; n < 2; ++n) _Pragma("unroll") for (int k = 0; k < 2; ++k) \
;         acc[ai][bj][m][n] = __builtin_amdgcn_mfma_f32_16x16x32_bf16(Bt[n][k], At[m][k], acc[ai][bj][m][n], 0, 0, 0); __builtin_amdgcn_s_setprio(0); } while (0)
; #define PG8_WAIT_V(n) asm volatile("s_waitcnt vmcnt(" #n ")" ::: "memory")
; #define PG8_WAIT_L(n) asm volatile("s_waitcnt lgkmcnt(" #n ")" ::: "memory")
; #define PG8_BAR __builtin_amdgcn_s_barrier()
; #define PG8_SCHED __builtin_amdgcn_sched_barrier(0)
; template <class Epi, class Sched>
; __device__ __forceinline__ void gemm_phase(const int tid, LAS unsigned char* lds, const Gemm g, const Sched& S, const Epi& E) {
;     ...
;             PG8_LDB(B0, 1, 0); PG8_LDB(B1, 1, 1); PG8_SCHED; PG8_LDA(At, 1, 0); PG8_STAGE(PG8_SA(0, 1), a2 + hstepA, voffA);
;             PG8_WAIT_V(8); PG8_WAIT_L(0); PG8_BAR; PG8_MMA(0, 0, At, B0); PG8_MMA(0, 1, At, B1); PG8_BAR; PG8_SCHED;
;             PG8_LDA(At, 1, 1); PG8_STAGE(PG8_SB(1, 0), b3, voffB); PG8_STAGE(PG8_SB(1, 1), b3 + hstepB, voffB); PG8_STAGE(PG8_SA(1, 0), a3, voffA);
;             PG8_WAIT_V(8); PG8_WAIT_L(0); PG8_BAR; PG8_MMA(1, 0, At, B0); PG8_MMA(1, 1, At, B1); PG8_BAR; PG8_SCHED;
;         }
;         if (wr == 0) PG8_BAR;
	s_add_i32 s67, 16, 0x18000
	s_add_i32 s76, 16, 0x1c000
	v_add_u32_e32 v78, s67, v180
	v_add_u32_e32 v178, s76, v180
	ds_read_b128 v[58:61], v78
	ds_read_b128 v[62:65], v78 offset:1024
	ds_read_b128 v[74:77], v78 offset:2048
	ds_read_b128 v[78:81], v78 offset:3072
	ds_read_b128 v[174:177], v178
	ds_read_b128 v[182:185], v178 offset:1024
	ds_read_b128 v[186:189], v178 offset:2048
	ds_read_b128 v[190:193], v178 offset:3072
	s_add_u32 s28, s28, 0x4000
	s_addc_u32 s29, s29, 0
	s_mov_b32 m0, s56
	ds_read_b128 v[204:207], v181 offset:32768
	ds_read_b128 v[208:211], v181 offset:33792
	ds_read_b128 v[212:215], v181 offset:34816
	ds_read_b128 v[216:219], v181 offset:35840
	ds_read_b128 v[220:223], v181 offset:36864
	ds_read_b128 v[236:239], v181 offset:37888
	ds_read_b128 v[244:247], v181 offset:38912
	ds_read_b128 v[248:251], v181 offset:39936
	global_load_lds_dwordx4 v146, s[28:29]
	s_mov_b32 m0, s57
	s_nop 0
	global_load_lds_dwordx4 v148, s[28:29]
	s_waitcnt vmcnt(8)
	s_waitcnt lgkmcnt(0)
	s_barrier
	s_setprio 1
	s_waitcnt lgkmcnt(0)
	v_mfma_f32_16x16x32_bf16 v[142:145], v[58:61], v[204:207], v[142:145]
	v_mfma_f32_16x16x32_bf16 v[138:141], v[74:77], v[204:207], v[138:141]
	v_mfma_f32_16x16x32_bf16 v[126:129], v[58:61], v[212:215], v[126:129]
	v_mfma_f32_16x16x32_bf16 v[122:125], v[74:77], v[212:215], v[122:125]
	v_mfma_f32_16x16x32_bf16 v[110:113], v[58:61], v[220:223], v[110:113]
	v_mfma_f32_16x16x32_bf16 v[106:109], v[74:77], v[220:223], v[106:109]
	v_mfma_f32_16x16x32_bf16 v[94:97], v[58:61], v[244:247], v[94:97]
	v_mfma_f32_16x16x32_bf16 v[90:93], v[74:77], v[244:247], v[90:93]
	v_mfma_f32_16x16x32_bf16 v[142:145], v[62:65], v[208:211], v[142:145]
	v_mfma_f32_16x16x32_bf16 v[138:141], v[78:81], v[208:211], v[138:141]
	v_mfma_f32_16x16x32_bf16 v[126:129], v[62:65], v[216:219], v[126:129]
	v_mfma_f32_16x16x32_bf16 v[122:125], v[78:81], v[216:219], v[122:125]
	v_mfma_f32_16x16x32_bf16 v[110:113], v[62:65], v[236:239], v[110:113]
	v_mfma_f32_16x16x32_bf16 v[106:109], v[78:81], v[236:239], v[106:109]
	v_mfma_f32_16x16x32_bf16 v[94:97], v[62:65], v[248:251], v[94:97]
	v_mfma_f32_16x16x32_bf16 v[90:93], v[78:81], v[248:251], v[90:93]
	v_mfma_f32_16x16x32_bf16 v[134:137], v[174:177], v[204:207], v[134:137]
	v_mfma_f32_16x16x32_bf16 v[130:133], v[186:189], v[204:207], v[130:133]
	v_mfma_f32_16x16x32_bf16 v[118:121], v[174:177], v[212:215], v[118:121]
	v_mfma_f32_16x16x32_bf16 v[114:117], v[186:189], v[212:215], v[114:117]
	v_mfma_f32_16x16x32_bf16 v[102:105], v[174:177], v[220:223], v[102:105]
	v_mfma_f32_16x16x32_bf16 v[98:101], v[186:189], v[220:223], v[98:101]
	v_mfma_f32_16x16x32_bf16 v[86:89], v[174:177], v[244:247], v[86:89]
	v_mfma_f32_16x16x32_bf16 v[82:85], v[186:189], v[244:247], v[82:85]
	v_mfma_f32_16x16x32_bf16 v[134:137], v[182:185], v[208:211], v[134:137]
	v_mfma_f32_16x16x32_bf16 v[130:133], v[190:193], v[208:211], v[130:133]
	v_mfma_f32_16x16x32_bf16 v[118:121], v[182:185], v[216:219], v[118:121]
	v_mfma_f32_16x16x32_bf16 v[114:117], v[190:193], v[216:219], v[114:117]
	v_mfma_f32_16x16x32_bf16 v[102:105], v[182:185], v[236:239], v[102:105]
	v_mfma_f32_16x16x32_bf16 v[98:101], v[190:193], v[236:239], v[98:101]
	v_mfma_f32_16x16x32_bf16 v[86:89], v[182:185], v[248:251], v[86:89]
	v_mfma_f32_16x16x32_bf16 v[82:85], v[190:193], v[248:251], v[82:85]
	s_setprio 0
	s_barrier
	s_add_u32 s28, s26, 0x8000
	s_addc_u32 s29, s27, 0
	s_add_i32 s67, s67, s54
	s_mov_b32 m0, s67
	ds_read_b128 v[204:207], v181 offset:49152
	ds_read_b128 v[208:211], v181 offset:50176
	ds_read_b128 v[212:215], v181 offset:51200
	ds_read_b128 v[216:219], v181 offset:52224
	ds_read_b128 v[220:223], v181 offset:53248
	ds_read_b128 v[236:239], v181 offset:54272
	ds_read_b128 v[244:247], v181 offset:55296
	ds_read_b128 v[248:251], v181 offset:56320
	global_load_lds_dwordx4 v0, s[28:29]
	s_add_i32 m0, s67, 0x2000
	s_add_u32 s26, s26, 0xc000
	s_addc_u32 s27, s27, 0
	global_load_lds_dwordx4 v150, s[28:29]
	s_add_i32 s28, s76, s54
	s_mov_b32 m0, s28
	s_nop 0
	global_load_lds_dwordx4 v0, s[26:27]
	s_add_i32 m0, s28, 0x2000
	s_nop 0
	global_load_lds_dwordx4 v150, s[26:27]
	s_mov_b32 m0, s58
	s_nop 0
	global_load_lds_dwordx4 v146, s[24:25]
	v_lshl_add_u64 v[178:179], s[24:25], 0, v[148:149]
	s_mov_b32 m0, s59
	s_nop 0
	global_load_lds_dwordx4 v[178:179], off
	s_waitcnt vmcnt(8)
	s_waitcnt lgkmcnt(0)
	s_barrier
	s_setprio 1
	s_waitcnt lgkmcnt(0)
	v_mfma_f32_16x16x32_bf16 v[70:73], v[58:61], v[204:207], v[70:73]
	v_mfma_f32_16x16x32_bf16 v[66:69], v[74:77], v[204:207], v[66:69]
	v_mfma_f32_16x16x32_bf16 v[46:49], v[58:61], v[212:215], v[46:49]
	v_mfma_f32_16x16x32_bf16 v[42:45], v[74:77], v[212:215], v[42:45]
	v_mfma_f32_16x16x32_bf16 v[30:33], v[58:61], v[220:223], v[30:33]
	v_mfma_f32_16x16x32_bf16 v[26:29], v[74:77], v[220:223], v[26:29]
	v_mfma_f32_16x16x32_bf16 v[14:17], v[58:61], v[244:247], v[14:17]
	v_mfma_f32_16x16x32_bf16 v[10:13], v[74:77], v[244:247], v[10:13]
	v_mfma_f32_16x16x32_bf16 v[70:73], v[62:65], v[208:211], v[70:73]
	v_mfma_f32_16x16x32_bf16 v[66:69], v[78:81], v[208:211], v[66:69]
	v_mfma_f32_16x16x32_bf16 v[46:49], v[62:65], v[216:219], v[46:49]
	v_mfma_f32_16x16x32_bf16 v[42:45], v[78:81], v[216:219], v[42:45]
	v_mfma_f32_16x16x32_bf16 v[30:33], v[62:65], v[236:239], v[30:33]
	v_mfma_f32_16x16x32_bf16 v[26:29], v[78:81], v[236:239], v[26:29]
	v_mfma_f32_16x16x32_bf16 v[14:17], v[62:65], v[248:251], v[14:17]
	v_mfma_f32_16x16x32_bf16 v[10:13], v[78:81], v[248:251], v[10:13]
	v_mfma_f32_16x16x32_bf16 v[54:57], v[174:177], v[204:207], v[54:57]
	v_mfma_f32_16x16x32_bf16 v[50:53], v[186:189], v[204:207], v[50:53]
	v_mfma_f32_16x16x32_bf16 v[38:41], v[174:177], v[212:215], v[38:41]
	v_mfma_f32_16x16x32_bf16 v[34:37], v[186:189], v[212:215], v[34:37]
	v_mfma_f32_16x16x32_bf16 v[22:25], v[174:177], v[220:223], v[22:25]
	v_mfma_f32_16x16x32_bf16 v[18:21], v[186:189], v[220:223], v[18:21]
	v_mfma_f32_16x16x32_bf16 v[6:9], v[174:177], v[244:247], v[6:9]
	v_mfma_f32_16x16x32_bf16 v[2:5], v[186:189], v[244:247], v[2:5]
	v_mfma_f32_16x16x32_bf16 v[54:57], v[182:185], v[208:211], v[54:57]
	v_mfma_f32_16x16x32_bf16 v[50:53], v[190:193], v[208:211], v[50:53]
	v_mfma_f32_16x16x32_bf16 v[38:41], v[182:185], v[216:219], v[38:41]
	v_mfma_f32_16x16x32_bf16 v[34:37], v[190:193], v[216:219], v[34:37]
	v_mfma_f32_16x16x32_bf16 v[22:25], v[182:185], v[236:239], v[22:25]
	v_mfma_f32_16x16x32_bf16 v[18:21], v[190:193], v[236:239], v[18:21]
	v_mfma_f32_16x16x32_bf16 v[6:9], v[182:185], v[248:251], v[6:9]
	v_mfma_f32_16x16x32_bf16 v[2:5], v[190:193], v[248:251], v[2:5]
	s_setprio 0
	s_barrier
	s_add_i32 s66, s66, 2
	s_add_u32 s64, s64, 0x10000
	s_addc_u32 s65, s65, 0
	s_add_u32 s6, s6, 0x10000
	s_addc_u32 s7, s7, 0
	s_cmp_gt_u32 s66, 29
	s_cbranch_scc0 .LBB0_135
	s_and_b64 vcc, exec, s[10:11]
	s_cbranch_vccz .LBB0_138
	s_barrier
